# v7 + one static s_setprio 1 for waves 4-7 during the two scan phases
# baseline (speedup 1.0000x reference)
; #define LAS __attribute__((address_space(3)))
; __device__ __forceinline__ void relaunder(Frame& F) { int t = mk_tid(); asm volatile("" : "+v"(t)); F.tid = t; F.lane = t & 63; F.wave = __builtin_amdgcn_readfirstlane(t >> 6); }
; __device__ __forceinline__ void mixer_hg2(const Args& a, Frame& F, bool ctx_out) {
;     relaunder(F);
;     float zf_ = 0.f; asm volatile("" : "+v"(zf_));
;     const f32x4 ZERO4 = {zf_, zf_, zf_, zf_};
;     constexpr int HD = 128, NH = 16, NEB = 2, C = 64, NCTX = CTXL / C, NCH = (CTXL + SEQ) / C, KS = HD / 32;
;     constexpr int QS = HD * 2 + 16, IMG = 64 * QS, PS = MX_PS;
;     constexpr int O_VT = 3 * IMG, O_P = O_VT + 64 * PS, O_ST = O_P + 64 * PS, O_END = O_ST + IMG;
;     static_assert(O_END <= RING_BYTES && MX_SWZ == 0, "mixer_hg2 LDS (padded images)");
;     const int lane = F.lane, w = F.wave, tid = F.tid, g = lane >> 4, i = lane & 15;
;     const int rg = w >> 1, cg = w & 1, nq0 = 16 * rg;
;     LAS unsigned char* const L = F.lds;
;     const bf16* act = (const bf16*)(a.ws + WS_ACT);
;     mx_bf16x8 bt0, bt1;
; #pragma unroll
;     for (int j = 0; j < 8; ++j) { bt0[j] = (8 * g + j <= i) ? (short)0x3F80 : (short)0; bt1[j] = (8 * g + j <= 16 + i) ? (short)0x3F80 : (short)0; }
;     for (int task = F.vcu; task < BATCH * NH * 2 * NEB; task += F.G) {
;         const int eb = task % NEB, dir = (task / NEB) & 1, h = (task / (2 * NEB)) % NH, b = task / (2 * NEB * NH);
;         bf16* O = (bf16*)(a.ws + (dir ? WS_OB : WS_OF));
;         const bf16* src0 = act;
;         const bf16* src1 = act + (size_t)(2 + 2 * dir) * ACT_STRIDE;
;         const bf16* src2 = act + (size_t)(1 + 2 * dir) * ACT_STRIDE;
;         const bf16* srcv = act + (size_t)5 * ACT_STRIDE;
;         const int vrow = tid & 63, vcc = tid >> 6, vs = dir ? 63 - vrow : vrow;
;         f32x4 accS[4];
; #pragma unroll
;         for (int te = 0; te < 4; ++te) accS[te] = ZERO4;
;         constexpr int PF = MX_PF_HG;
;         static_assert(NCH % PF == 0, "prefetch depth must divide the chunk count");
;         v4u rq[PF][3][2]; v4u rv[PF];
.LBB0_507:
	s_andn2_b64 vcc, exec, s[8:9]
	s_cbranch_vccnz .LBB0_570
	s_getreg_b32 s6, hwreg(HW_REG_HW_ID, 0, 6)
	s_lshl_b32 s6, s6, 2
	s_add_i32 s6, s6, 0
	s_add_i32 s6, s6, 0x20540
	v_mov_b32_e32 v0, s6
	ds_read_b32 v0, v0
	v_readlane_b32 s8, v254, 25
	v_mbcnt_lo_u32_b32 v3, -1, 0
	v_mbcnt_hi_u32_b32 v3, -1, v3
	v_readlane_b32 s9, v254, 26
	v_mov_b32_e32 v2, v1
	s_waitcnt lgkmcnt(0)
	v_readfirstlane_b32 s6, v0
	s_andn2_b64 vcc, exec, s[8:9]
	s_nop 0
	v_lshl_add_u32 v0, s6, 6, v3
	s_nop 0
	v_readfirstlane_b32 s6, v0
	s_cbranch_vccnz .LBB0_524
	s_waitcnt vmcnt(0)
	v_mov_b64_e32 v[4:5], s[0:1]
	flat_load_dwordx2 v[14:15], v[4:5] offset:152
	v_and_b32_e32 v18, 15, v0
	v_bfe_u32 v19, v0, 4, 2
	v_or_b32_e32 v11, 16, v18
	v_lshlrev_b32_e32 v12, 3, v19
	v_lshlrev_b32_e32 v8, 4, v0
	v_cmp_gt_u32_e32 vcc, v12, v11
	v_mov_b32_e32 v31, 0x3f80
	v_lshlrev_b32_e32 v6, 3, v0
	v_bfe_u32 v9, v0, 2, 2
	v_lshrrev_b32_e32 v10, 1, v0
	v_and_b32_e32 v186, 0xf0, v8
	v_cndmask_b32_e64 v8, v31, 0, vcc
	v_cmp_lt_u32_e32 vcc, v12, v11
	v_and_b32_e32 v184, 0x78, v6
	v_and_or_b32 v6, v10, 24, v9
	v_cndmask_b32_e32 v9, 0, v31, vcc
	v_cmp_gt_u32_e32 vcc, v12, v18
	v_and_b32_e32 v185, 63, v0
	s_ashr_i32 s6, s6, 6
	s_cmp_lt_u32 s6, 4
	s_cbranch_scc1 .Lhg_prio_skip
	s_setprio 1
.Lhg_prio_skip:
	v_ashrrev_i32_e32 v7, 3, v0
	v_cndmask_b32_e64 v10, v31, 0, vcc
	v_cmp_lt_u32_e32 vcc, v12, v18
	v_or_b32_e32 v21, 2, v12
	v_and_b32_e32 v16, -8, v7
	s_lshl_b32 s9, s6, 5
	v_lshlrev_b32_e32 v7, 3, v185
	v_cndmask_b32_e32 v13, 0, v31, vcc
	v_or_b32_e32 v20, 3, v12
	v_cmp_gt_u32_e32 vcc, v21, v11
	v_and_or_b32 v27, v7, 16, s9
	v_and_b32_e32 v28, 8, v7
	s_mov_b32 s10, 0x5040100
	v_cndmask_b32_e64 v7, v31, 0, vcc
	v_cmp_gt_u32_e32 vcc, v20, v11
	v_mul_u32_u24_e32 v26, 0x120, v6
	v_perm_b32 v6, v9, v8, s10
	v_cndmask_b32_e64 v8, v31, 0, vcc
	v_cmp_gt_u32_e32 vcc, v21, v18
	v_or_b32_e32 v23, 4, v12
	v_or_b32_e32 v22, 5, v12
	v_cndmask_b32_e64 v9, v31, 0, vcc
	v_cmp_gt_u32_e32 vcc, v20, v18
	v_perm_b32 v10, v13, v10, s10
	v_or_b32_e32 v25, 6, v12
	v_cndmask_b32_e64 v13, v31, 0, vcc
	v_cmp_gt_u32_e32 vcc, v23, v11
	v_or_b32_e32 v24, 7, v12
	v_readlane_b32 s24, v254, 62
	v_cndmask_b32_e64 v20, v31, 0, vcc
	v_cmp_gt_u32_e32 vcc, v22, v11
	s_lshl_b32 s8, s6, 3
	s_add_i32 s6, s9, s24
	v_cndmask_b32_e64 v21, v31, 0, vcc
	v_cmp_gt_u32_e32 vcc, v23, v18
	s_add_i32 s7, s9, 0
	v_add3_u32 v26, 0, v26, v27
	v_cndmask_b32_e64 v23, v31, 0, vcc
	v_cmp_gt_u32_e32 vcc, v22, v18
	v_add_u32_e32 v27, s6, v12
	v_bfi_b32 v229, -16, s8, v0
	v_cndmask_b32_e64 v22, v31, 0, vcc
	v_cmp_gt_u32_e32 vcc, v25, v11
	s_movk_i32 s25, 0x120
	v_perm_b32 v7, v8, v7, s10
	v_cndmask_b32_e64 v29, v31, 0, vcc
	v_cmp_gt_u32_e32 vcc, v24, v11
	v_perm_b32 v8, v21, v20, s10
	v_and_b32_e32 v232, 48, v0
	v_cndmask_b32_e64 v30, v31, 0, vcc
	v_cmp_gt_u32_e32 vcc, v25, v18
	v_ashrrev_i32_e32 v237, 4, v0
	v_add_u32_e32 v0, 0x200, v0
	v_cndmask_b32_e64 v25, v31, 0, vcc
	v_cmp_gt_u32_e32 vcc, v24, v18
	v_perm_b32 v11, v13, v9, s10
	v_perm_b32 v9, v30, v29, s10
	v_cndmask_b32_e64 v24, v31, 0, vcc
	v_add_u32_e32 v31, s7, v12
	s_mov_b64 s[6:7], 0xd000000
	s_waitcnt vmcnt(0) lgkmcnt(0)
	v_lshl_add_u64 v[188:189], v[14:15], 0, s[6:7]
	s_mov_b64 s[6:7], 0x22400000
	v_lshl_add_u64 v[190:191], v[14:15], 0, s[6:7]
	v_mul_lo_u32 v14, v229, s25
	v_add_u32_e32 v230, 0, v14
	s_and_b32 s6, s9, 32
	v_lshlrev_b32_e32 v14, 2, v19
	v_or_b32_e32 v19, s6, v14
	v_or_b32_e32 v21, 2, v19
	v_cmp_gt_i32_e64 s[12:13], v21, v229
	v_or_b32_e32 v21, 3, v19
	v_cmp_gt_i32_e64 s[14:15], v21, v229
	v_lshlrev_b32_e32 v21, 7, v229
	v_sub_u32_e32 v233, v230, v21
	v_add_u32_e32 v233, 0x10000, v233
	v_or_b32_e32 v21, 17, v19
	s_movk_i32 s7, 0xa0
	v_perm_b32 v12, v22, v23, s10
	v_perm_b32 v13, v24, v25, s10
	v_or_b32_e32 v20, 16, v19
	v_cmp_gt_i32_e64 s[8:9], v19, v229
	v_cmp_lt_i32_e64 s[10:11], v19, v229
	v_lshlrev_b32_e32 v234, 1, v19
	v_cmp_gt_i32_e64 s[18:19], v21, v229
	v_or_b32_e32 v21, 18, v19
	v_or_b32_e32 v19, 19, v19
	v_ashrrev_i32_e32 v238, 4, v0
	v_mul_lo_u32 v0, v16, s7
	v_lshlrev_b32_e32 v187, 1, v185
	v_ashrrev_i32_e32 v17, 31, v16
	v_or_b32_e32 v15, s6, v18
	v_cmp_gt_i32_e64 s[22:23], v19, v229
	v_add_u32_e32 v241, 0, v0
	v_mul_u32_u24_e32 v19, 0x120, v18
	v_mad_u32_u24 v18, v18, s7, 0
	v_mov_b32_e32 v0, s24
	v_mov_b32_e32 v3, v2
	v_mov_b32_e32 v4, v2
	v_mov_b32_e32 v5, v2
	v_xor_b32_e32 v228, 0x7e, v187
	v_mad_u32_u24 v231, v15, s25, 0
	v_cmp_gt_i32_e64 s[16:17], v20, v229
	v_cmp_gt_i32_e64 s[20:21], v21, v229
	v_lshlrev_b32_e32 v235, 1, v20
	v_sub_u32_e32 v236, 63, v229
	v_sub_u32_e32 v239, 63, v237
	v_sub_u32_e32 v240, 63, v238
	v_mad_u32_u24 v242, v15, s25, v0
	v_mad_u32_u24 v243, v15, s7, 0
	v_lshlrev_b64 v[192:193], 1, v[16:17]
	s_lshl_b32 s28, s6, 1
	v_lshlrev_b32_e32 v0, 1, v14
	v_add_u32_e32 v244, v18, v232
	v_add_u32_e32 v245, v26, v28
	v_add_u32_e32 v246, v27, v19
	v_add_u32_e32 v247, v31, v19
	v_readlane_b32 s6, v254, 4
	s_branch .LBB0_511

; __device__ __forceinline__ int mk_tid() { return mk_wave() * 64 + mk_lane(); }
; __device__ __forceinline__ unsigned xb_ld(unsigned* p)              { return __hip_atomic_load(p, __ATOMIC_RELAXED, __HIP_MEMORY_SCOPE_AGENT); }
; __device__ __forceinline__ unsigned xb_add(unsigned* p, unsigned v) { return __hip_atomic_fetch_add(p, v, __ATOMIC_RELAXED, __HIP_MEMORY_SCOPE_AGENT); }
; #define XB_SPIN(cond, bar) do { unsigned _sp = 0; while (cond) { __builtin_amdgcn_s_sleep(1); \
;     if ((++_sp & 255u) == 0u) { if (xb_ld(&(bar)[XB_TMO])) break; if (_sp > XB_SPIN_CAP) { atomicAdd(&(bar)[XB_TMO], 1u); break; } } } } while (0)
; __device__ __forceinline__ void xcd_barrier(const XcdBarrier& b) {
;     asm volatile("s_waitcnt vmcnt(0)" ::: "memory");
;     __syncthreads();
;     if (mk_tid() == 0) {
;         unsigned* bar = b.bar;
;         __builtin_amdgcn_s_waitcnt(0);
;         unsigned nloc = b.st[0], nx = b.st[1];
;         if (nloc == 0u) { xcd_barrier_complete(bar, b.x, nloc, nx); b.st[0] = nloc; b.st[1] = nx; }
;         const unsigned old = xb_add(&bar[XB_XSUB(b.x)], 1u);
;         const unsigned gen = old / nloc;
;         if (old + 1u == (gen + 1u) * nloc) {
;             __builtin_amdgcn_fence(__ATOMIC_RELEASE, "agent");
;             asm volatile("s_waitcnt vmcnt(0)" ::: "memory");
;             const unsigned og = xb_add(&bar[XB_TOP], 1u);
;             const unsigned tg = og / nx;
;             if (og + 1u == (tg + 1u) * nx) xb_add(&bar[XB_TOPGEN], 1u);
;             else XB_SPIN(xb_ld(&bar[XB_TOPGEN]) == tg, bar);
;             __builtin_amdgcn_fence(__ATOMIC_ACQUIRE, "agent");
;             xb_add(&bar[XB_XGEN(b.x)], 1u);
;             asm volatile("s_waitcnt vmcnt(0)" ::: "memory");
;         } else {
;             XB_SPIN(xb_ld(&bar[XB_XGEN(b.x)]) == gen, bar);
.LBB0_524:
	s_setprio 0
	v_readlane_b32 s6, v255, 13
	s_or_b32 s6, s6, 5
	s_cmp_ge_i32 s6, s61
	s_cbranch_scc1 .LBB0_570
	v_readlane_b32 s48, v254, 5
	v_readlane_b32 s49, v254, 6
	v_readlane_b32 s7, v254, 7
	s_waitcnt vmcnt(0)
	s_barrier
	s_getreg_b32 s8, hwreg(HW_REG_HW_ID, 0, 6)
	s_lshl_b32 s8, s8, 2
	s_add_i32 s8, s8, 0
	s_add_i32 s8, s8, 0x20540
	v_mov_b32_e32 v0, s8
	ds_read_b32 v0, v0
	s_waitcnt lgkmcnt(0)
	v_readfirstlane_b32 s8, v0
	v_mbcnt_lo_u32_b32 v0, -1, 0
	v_mbcnt_hi_u32_b32 v0, -1, v0
	s_lshl_b32 s8, s8, 6
	v_sub_u32_e32 v0, 0, v0
	v_cmp_eq_u32_e32 vcc, s8, v0
	s_and_saveexec_b64 s[78:79], vcc
	s_cbranch_execz .LBB0_569
	v_readlane_b32 s8, v254, 60
	s_waitcnt vmcnt(0) expcnt(0) lgkmcnt(0)
	s_nop 0
	v_mov_b32_e32 v0, s8
	ds_read_b32 v2, v0
	v_readlane_b32 s8, v254, 61
	s_waitcnt lgkmcnt(0)
	v_cmp_ne_u32_e32 vcc, 0, v2
	v_mov_b32_e32 v0, s8
	ds_read_b32 v0, v0
	s_cbranch_vccnz .LBB0_540
	v_readlane_b32 s8, v254, 2
	v_readlane_b32 s9, v254, 3
	s_load_dwordx2 s[12:13], s[8:9], 0x4
	s_add_u32 s8, s48, 0x1000
	s_addc_u32 s9, s49, 0
	s_add_u32 s10, s48, 0x1100
	s_addc_u32 s11, s49, 0
	s_waitcnt lgkmcnt(0)
	s_mul_i32 s33, s12, s3
	s_add_u32 s12, s48, 0x1200
	s_mul_i32 s33, s33, s13
	s_addc_u32 s13, s49, 0
	s_add_u32 s14, s48, 0x1300
	s_addc_u32 s15, s49, 0
	s_mov_b32 s36, 1
	s_mov_b64 s[16:17], 0
	s_branch .LBB0_530

; #define LAS __attribute__((address_space(3)))
;     ...
;     const int lane = F.lane, w = F.wave, tid = F.tid, g = lane >> 4, i = lane & 15;
;     const int rg = w >> 1, cg = w & 1, nq0 = 16 * rg;
;     LAS unsigned char* const L = F.lds;
;     const bf16* act = (const bf16*)(a.ws + WS_ACT);
;     for (int task = F.vcu; task < BATCH * NH * 2 * NEB; task += F.G) {
;         const int eb = task % NEB, dir = (task / NEB) & 1, h = (task / (2 * NEB)) % NH, b = task / (2 * NEB * NH);
;         bf16* O = (bf16*)(a.ws + (dir ? WS_OB : WS_OF));
;         const bf16* src0 = act;
;         const bf16* src1 = act + (size_t)(HG ? (2 + 2 * dir) : 1) * ACT_STRIDE;
;         const bf16* src2 = act + (size_t)(1 + 2 * dir) * ACT_STRIDE;
;         const bf16* srcv = act + (size_t)(HG ? 5 : 2) * ACT_STRIDE;
;         float lg2 = 0.f;
;         if (!HG) { const float x = a.in[10][(j_layer * 2 + dir) * 8 + h]; lg2 = -log1pf(expf(-x)) * 1.4426950408889634f; }
;         const float r1 = HG ? 1.f : exp2f((float)(nq0 + i - 63) * lg2), r2 = HG ? 1.f : exp2f((float)(nq0 + i + 1) * lg2), cdec = HG ? 1.f : exp2f(64.f * lg2);
;         const int vrow = tid & 63, vcc = tid >> 6;
;         const int vs = dir ? 63 - vrow : vrow;
;         const float kdec = HG ? 1.f : exp2f((float)(63 - vs) * lg2);
;         f32x4 accS[DT][4];
; #pragma unroll
;         for (int td = 0; td < DT; ++td)
; #pragma unroll
;             for (int te = 0; te < 4; ++te) accS[td][te] = ZERO4;
;         constexpr int NPQ = HG ? 2 : 4;
;         constexpr int PF = HG ? MX_PF_HG : MX_PF_RET;
;         static_assert(NCH % PF == 0, "prefetch depth must divide the chunk count");
;         v4u rq[PF][HG ? 3 : 2][NPQ]; v4u rv[PF];
;     ...
;         __syncthreads();
;         for (int u = tid; u < IMG / 16; u += NWAVES * 64) { const unsigned zu_ = __builtin_bit_cast(unsigned, zf_); *(LAS v4u*)(L + O_ST + u * 16) = (v4u){zu_, zu_, zu_, zu_}; }
.LBB0_795:
	s_andn2_b64 vcc, exec, s[6:7]
	s_cbranch_vccnz .LBB0_855
	s_getreg_b32 s6, hwreg(HW_REG_HW_ID, 0, 6)
	s_lshl_b32 s6, s6, 2
	s_add_i32 s6, s6, 0
	s_add_i32 s6, s6, 0x20540
	v_mov_b32_e32 v0, s6
	ds_read_b32 v0, v0
	v_mbcnt_lo_u32_b32 v3, -1, 0
	v_mbcnt_hi_u32_b32 v3, -1, v3
	v_mov_b32_e32 v2, v1
	s_waitcnt lgkmcnt(0)
	v_readfirstlane_b32 s6, v0
	s_nop 1
	v_lshl_add_u32 v0, s6, 6, v3
	v_readlane_b32 s6, v254, 25
	v_readlane_b32 s7, v254, 26
	s_andn2_b64 vcc, exec, s[6:7]
	v_readfirstlane_b32 s24, v0
	s_cbranch_vccnz .LBB0_809
	s_waitcnt vmcnt(0)
	v_mov_b64_e32 v[4:5], s[0:1]
	s_waitcnt vmcnt(0)
	flat_load_dwordx2 v[6:7], v[4:5] offset:152
	s_ashr_i32 s8, s24, 6
	s_cmp_lt_u32 s8, 4
	s_cbranch_scc1 .Lret_prio_skip
	s_setprio 1
.Lret_prio_skip:
	v_ashrrev_i32_e32 v16, 31, v0
	v_add_u32_e32 v17, 0x200, v0
	s_lshl_b32 s9, s8, 3
	s_lshl_b32 s8, s8, 5
	v_lshrrev_b32_e32 v16, 27, v16
	v_ashrrev_i32_e32 v19, 31, v17
	s_mov_b64 s[26:27], 0xd000000
	v_and_b32_e32 v11, 15, v0
	v_readlane_b32 s29, v255, 0
	s_and_b32 s25, s8, 32
	v_add_u32_e32 v16, v0, v16
	v_lshrrev_b32_e32 v19, 27, v19
	v_mov_b32_e32 v15, s29
	s_movk_i32 s12, 0x220
	v_or_b32_e32 v23, s25, v11
	v_ashrrev_i32_e32 v149, 5, v16
	v_and_b32_e32 v16, 0xffffffe0, v16
	v_add_u32_e32 v19, v17, v19
	v_mad_u32_u24 v155, v23, s12, v15
	v_sub_u32_e32 v15, v0, v16
	v_and_b32_e32 v16, 0xffffffe0, v19
	v_bfe_u32 v9, v0, 4, 2
	v_bfe_u32 v12, v0, 2, 2
	v_lshrrev_b32_e32 v13, 1, v0
	v_lshlrev_b32_e32 v10, 2, v9
	v_bfi_b32 v119, -16, s9, v0
	s_movk_i32 s28, 0xa0
	v_lshlrev_b32_e32 v14, 3, v0
	v_lshlrev_b32_e32 v18, 3, v9
	v_and_or_b32 v12, v13, 24, v12
	v_subrev_u32_e32 v20, 63, v119
	v_add_u32_e32 v21, 1, v119
	v_mul_lo_u32 v22, v119, s12
	v_or_b32_e32 v24, s25, v10
	v_mul_lo_u32 v25, v119, s28
	v_readlane_b32 s13, v254, 63
	v_ashrrev_i32_e32 v8, 3, v0
	v_and_b32_e32 v13, 8, v14
	v_and_b32_e32 v148, 8, v18
	v_mul_u32_u24_e32 v12, 0x220, v12
	v_cvt_f32_i32_e32 v150, v20
	v_cvt_f32_i32_e32 v151, v21
	v_add_u32_e32 v152, 0, v22
	v_or_b32_e32 v20, 2, v24
	v_add_u32_e32 v154, s13, v25
	v_lshlrev_b32_e32 v22, 1, v24
	v_or_b32_e32 v25, 16, v24
	v_readlane_b32 s6, v255, 14
	s_andn2_b32 s24, s24, 63
	v_and_b32_e32 v8, -8, v8
	v_add3_u32 v12, 0, v12, v13
	v_add_u32_e32 v13, s29, v148
	v_mad_u32_u24 v153, v23, s12, 0
	v_ashrrev_i32_e32 v156, 5, v19
	v_cmp_gt_i32_e64 s[12:13], v20, v119
	v_and_b32_e32 v19, 0x50, v22
	v_lshlrev_b32_e32 v20, 1, v25
	v_readlane_b32 s7, v255, 15
	s_lshl_b32 s33, s6, 4
	s_movk_i32 s6, 0x880
	v_and_b32_e32 v117, 48, v0
	v_ashrrev_i32_e32 v9, 31, v8
	v_cmp_gt_i32_e64 s[8:9], v24, v119
	v_cmp_lt_i32_e64 s[10:11], v24, v119
	v_or_b32_e32 v21, 3, v24
	v_or_b32_e32 v26, 17, v24
	v_or_b32_e32 v27, 18, v24
	v_or_b32_e32 v24, 19, v24
	v_lshlrev_b32_e32 v157, 3, v15
	v_add_u32_e32 v158, v154, v19
	v_and_b32_e32 v19, 0x70, v20
	v_lshlrev_b32_e32 v112, 4, v15
	v_mul_lo_u32 v165, v8, s28
	v_and_or_b32 v14, v14, 16, s24
	v_and_b32_e32 v113, 63, v0
	v_mov_b32_e32 v3, v2
	v_mov_b32_e32 v4, v2
	v_mov_b32_e32 v5, v2
	s_waitcnt vmcnt(0) lgkmcnt(0)
	v_lshl_add_u64 v[106:107], v[6:7], 0, s[26:27]
	s_mov_b64 s[26:27], 0x11400000
	v_lshl_add_u64 v[108:109], v[6:7], 0, s[26:27]
	s_mov_b64 s[26:27], 0x15800000
	v_lshl_add_u64 v[110:111], v[6:7], 0, s[26:27]
	v_add_u32_e32 v7, 0x400, v0
	v_sub_u32_e32 v6, v17, v16
	v_ashrrev_i32_e32 v16, 31, v7
	v_lshrrev_b32_e32 v16, 27, v16
	v_add_u32_e32 v16, v7, v16
	v_ashrrev_i32_e32 v161, 5, v16
	v_and_b32_e32 v16, 0xffffffe0, v16
	v_sub_u32_e32 v7, v7, v16
	v_add_u32_e32 v16, 0x600, v0
	v_ashrrev_i32_e32 v17, 31, v16
	v_lshrrev_b32_e32 v17, 27, v17
	v_add_u32_e32 v17, v16, v17
	v_readlane_b32 s26, v255, 1
	v_lshlrev_b32_e32 v160, 3, v6
	v_ashrrev_i32_e32 v163, 5, v17
	v_and_b32_e32 v17, 0xffffffe0, v17
	v_lshlrev_b32_e32 v114, 4, v6
	v_mov_b32_e32 v6, s26
	v_sub_u32_e32 v16, v16, v17
	v_mad_u32_u24 v167, v11, s28, v6
	v_mad_u32_u24 v168, v23, s28, v6
	v_and_b32_e32 v6, 16, v18
	v_lshlrev_b32_e32 v162, 3, v7
	v_lshlrev_b32_e32 v164, 3, v16
	v_lshlrev_b32_e32 v116, 4, v7
	v_lshlrev_b32_e32 v118, 4, v16
	v_add_u32_e32 v7, 0xa00, v167
	v_add_u32_e32 v15, 0x1400, v167
	v_add_u32_e32 v16, 0x1e00, v167
	v_add3_u32 v6, v13, v6, s24
	v_mul_u32_u24_e32 v11, 0x220, v11
	v_bitop3_b32 v115, v0, 63, v0 bitop3:0xc
	v_cmp_gt_i32_e64 s[6:7], s6, v0
	v_cmp_gt_i32_e64 s[14:15], v21, v119
	v_cmp_gt_i32_e64 s[16:17], v25, v119
	v_cmp_gt_i32_e64 s[18:19], v26, v119
	v_cmp_gt_i32_e64 s[20:21], v27, v119
	v_cmp_gt_i32_e64 s[22:23], v24, v119
	v_add_u32_e32 v159, v154, v19
	v_add_u32_e32 v166, s26, v165
	v_add_u32_e32 v169, 0xfffffe00, v0
	v_lshl_add_u32 v170, v0, 4, s29
	v_lshlrev_b64 v[120:121], 1, v[8:9]
	s_lshl_b32 s84, s25, 1
	v_lshlrev_b32_e32 v0, 1, v10
	v_add_u32_e32 v171, v7, v117
	v_add_u32_e32 v172, v15, v117
	v_add_u32_e32 v173, v16, v117
	v_add_u32_e32 v174, v12, v14
	v_add_u32_e32 v175, v6, v11
	v_readlane_b32 s44, v254, 4
	s_branch .LBB0_799

; __device__ __forceinline__ int mk_tid() { return mk_wave() * 64 + mk_lane(); }
; __device__ __forceinline__ unsigned xb_ld(unsigned* p)              { return __hip_atomic_load(p, __ATOMIC_RELAXED, __HIP_MEMORY_SCOPE_AGENT); }
; __device__ __forceinline__ unsigned xb_add(unsigned* p, unsigned v) { return __hip_atomic_fetch_add(p, v, __ATOMIC_RELAXED, __HIP_MEMORY_SCOPE_AGENT); }
; #define XB_SPIN(cond, bar) do { unsigned _sp = 0; while (cond) { __builtin_amdgcn_s_sleep(1); \
;     if ((++_sp & 255u) == 0u) { if (xb_ld(&(bar)[XB_TMO])) break; if (_sp > XB_SPIN_CAP) { atomicAdd(&(bar)[XB_TMO], 1u); break; } } } } while (0)
; __device__ __forceinline__ void xcd_barrier(const XcdBarrier& b) {
;     asm volatile("s_waitcnt vmcnt(0)" ::: "memory");
;     __syncthreads();
;     if (mk_tid() == 0) {
;         unsigned* bar = b.bar;
;         __builtin_amdgcn_s_waitcnt(0);
;         unsigned nloc = b.st[0], nx = b.st[1];
;         if (nloc == 0u) { xcd_barrier_complete(bar, b.x, nloc, nx); b.st[0] = nloc; b.st[1] = nx; }
;         const unsigned old = xb_add(&bar[XB_XSUB(b.x)], 1u);
;         const unsigned gen = old / nloc;
;         if (old + 1u == (gen + 1u) * nloc) {
;             __builtin_amdgcn_fence(__ATOMIC_RELEASE, "agent");
;             asm volatile("s_waitcnt vmcnt(0)" ::: "memory");
;             const unsigned og = xb_add(&bar[XB_TOP], 1u);
;             const unsigned tg = og / nx;
;             if (og + 1u == (tg + 1u) * nx) xb_add(&bar[XB_TOPGEN], 1u);
;             else XB_SPIN(xb_ld(&bar[XB_TOPGEN]) == tg, bar);
;             __builtin_amdgcn_fence(__ATOMIC_ACQUIRE, "agent");
;             xb_add(&bar[XB_XGEN(b.x)], 1u);
;             asm volatile("s_waitcnt vmcnt(0)" ::: "memory");
;         } else {
;             XB_SPIN(xb_ld(&bar[XB_XGEN(b.x)]) == gen, bar);
.LBB0_809:
	s_setprio 0
	v_readlane_b32 s6, v255, 13
	s_or_b32 s33, s6, 5
	s_cmp_ge_i32 s33, s61
	s_cbranch_scc1 .LBB0_855
	v_readlane_b32 s40, v254, 5
	v_readlane_b32 s41, v254, 6
	v_readlane_b32 s44, v254, 7
	s_waitcnt vmcnt(0)
	s_waitcnt lgkmcnt(0)
	s_barrier
	s_getreg_b32 s6, hwreg(HW_REG_HW_ID, 0, 6)
	s_lshl_b32 s6, s6, 2
	s_add_i32 s6, s6, 0
	s_add_i32 s6, s6, 0x20540
	v_mov_b32_e32 v0, s6
	ds_read_b32 v0, v0
	s_waitcnt lgkmcnt(0)
	v_readfirstlane_b32 s6, v0
	v_mbcnt_lo_u32_b32 v0, -1, 0
	v_mbcnt_hi_u32_b32 v0, -1, v0
	s_lshl_b32 s6, s6, 6
	v_sub_u32_e32 v0, 0, v0
	v_cmp_eq_u32_e32 vcc, s6, v0
	s_and_saveexec_b64 s[48:49], vcc
	s_cbranch_execz .LBB0_854
	v_readlane_b32 s6, v254, 60
	s_waitcnt vmcnt(0) expcnt(0) lgkmcnt(0)
	s_nop 0
	v_mov_b32_e32 v0, s6
	ds_read_b32 v2, v0
	v_readlane_b32 s6, v254, 61
	s_waitcnt lgkmcnt(0)
	v_cmp_ne_u32_e32 vcc, 0, v2
	v_mov_b32_e32 v0, s6
	ds_read_b32 v0, v0
	s_cbranch_vccnz .LBB0_825
	v_readlane_b32 s6, v254, 2
	v_readlane_b32 s7, v254, 3
	s_load_dwordx2 s[10:11], s[6:7], 0x4
	s_add_u32 s6, s40, 0x1000
	s_addc_u32 s7, s41, 0
	s_add_u32 s8, s40, 0x1100
	s_addc_u32 s9, s41, 0
	s_waitcnt lgkmcnt(0)
	s_mul_i32 s34, s10, s3
	s_add_u32 s10, s40, 0x1200
	s_mul_i32 s34, s34, s11
	s_addc_u32 s11, s41, 0
	s_add_u32 s12, s40, 0x1300
	s_addc_u32 s13, s41, 0
	s_mov_b32 s35, 1
	s_mov_b64 s[14:15], 0
	s_branch .LBB0_815
